# LRU x_b staging loops unrolled: 9 loads in flight instead of serialized load-wait-write
# speedup vs baseline: 1.0066x; 1.0066x over previous
; #define LAS __attribute__((address_space(3)))
; template <bool PASS2>
; __device__ __forceinline__ void lru_item(const Frame& F, const Args& a, int item) {
;     ...
;     for (int idx = F.tid; idx < 259 * 16; idx += 512) { const int row = idx >> 4, ch = idx & 15; const int t = t0 - 1 + row; u32x4 v = (u32x4){0u, 0u, 0u, 0u};
;         if (t >= 0 && t < SEQ) v = *(const u32x4*)(proj + (rowbase + t) * NIN + C_XB + n * 128 + 8 * ch);
;         *(LAS u32x4*)(R0 + row * AT_PITCH + 16 * ch) = v; }
.LBB0_143:
	s_mul_hi_i32 s4, s55, 0x2aaaaaab
	s_ashr_i32 s5, s4, 1
	s_lshr_b32 s6, s4, 31
	s_add_i32 s5, s5, s6
	s_mul_i32 s7, s5, 12
	s_sub_i32 s13, s55, s7
	s_ashr_i32 s7, s5, 31
	s_lshr_b32 s7, s7, 28
	s_add_i32 s7, s5, s7
	s_and_b32 s7, s7, -16
	s_ashr_i32 s4, s4, 5
	s_sub_i32 s56, s5, s7
	s_add_i32 s38, s4, s6
	s_lshl_b32 s57, s56, 8
	s_ashr_i32 s39, s38, 31
	s_lshl_b32 s4, s13, 7
	s_lshl_b64 s[6:7], s[38:39], 12
	s_ashr_i32 s5, s4, 31
	v_add_u32_e32 v8, s57, v112
	s_mov_b64 s[8:9], 0
	v_mov_b32_e32 v9, v114
	v_mov_b32_e32 v10, v113
	s_waitcnt vmcnt(0)
	s_barrier
	v_cmp_gt_u32_e64 s[8:9], 48, v144
	v_add_u32_e32 v9, 0x100, v8
	v_mov_b32_e32 v44, 0
	v_mov_b32_e32 v45, 0
	v_mov_b32_e32 v46, 0
	v_mov_b32_e32 v47, 0
	v_cmp_gt_u32_e32 vcc, s46, v9
	s_and_b64 vcc, vcc, s[8:9]
	s_and_saveexec_b64 s[10:11], vcc
	s_cbranch_execz .Lstg_p1a_8
	v_or_b32_e32 v6, s6, v9
	v_mov_b64_e32 v[4:5], s[22:23]
	v_mad_u64_u32 v[4:5], s[14:15], v6, s47, v[4:5]
	v_mad_i32_i24 v5, s7, v118, v5
	v_lshl_add_u64 v[4:5], s[4:5], 1, v[4:5]
	v_lshl_add_u64 v[4:5], v[4:5], 0, v[94:95]
	v_add_co_u32_e32 v4, vcc, 0xe402000, v4
	s_nop 1
	v_addc_co_u32_e32 v5, vcc, 0, v5, vcc
	global_load_dwordx4 v[44:47], v[4:5], off offset:1024
.Lstg_p1a_8:
	s_or_b64 exec, exec, s[10:11]
	v_mov_b32_e32 v12, 0
	v_mov_b32_e32 v13, 0
	v_mov_b32_e32 v14, 0
	v_mov_b32_e32 v15, 0
	v_cmp_gt_u32_e32 vcc, s46, v8
	s_and_saveexec_b64 s[10:11], vcc
	s_cbranch_execz .Lstg_p1a_0
	v_or_b32_e32 v6, s6, v8
	v_mov_b64_e32 v[4:5], s[22:23]
	v_mad_u64_u32 v[4:5], s[14:15], v6, s47, v[4:5]
	v_mad_i32_i24 v5, s7, v118, v5
	v_lshl_add_u64 v[4:5], s[4:5], 1, v[4:5]
	v_lshl_add_u64 v[4:5], v[4:5], 0, v[94:95]
	v_add_co_u32_e32 v4, vcc, 0xe402000, v4
	s_nop 1
	v_addc_co_u32_e32 v5, vcc, 0, v5, vcc
	global_load_dwordx4 v[12:15], v[4:5], off offset:1024
.Lstg_p1a_0:
	s_or_b64 exec, exec, s[10:11]
	v_add_u32_e32 v8, 32, v8
	v_mov_b32_e32 v16, 0
	v_mov_b32_e32 v17, 0
	v_mov_b32_e32 v18, 0
	v_mov_b32_e32 v19, 0
	v_cmp_gt_u32_e32 vcc, s46, v8
	s_and_saveexec_b64 s[10:11], vcc
	v_or_b32_e32 v6, s6, v8
	v_mov_b64_e32 v[4:5], s[22:23]
	v_mad_u64_u32 v[4:5], s[14:15], v6, s47, v[4:5]
	v_mad_i32_i24 v5, s7, v118, v5
	v_lshl_add_u64 v[4:5], s[4:5], 1, v[4:5]
	v_lshl_add_u64 v[4:5], v[4:5], 0, v[94:95]
	v_add_co_u32_e32 v4, vcc, 0xe402000, v4
	s_nop 1
	v_addc_co_u32_e32 v5, vcc, 0, v5, vcc
	global_load_dwordx4 v[16:19], v[4:5], off offset:1024
	s_or_b64 exec, exec, s[10:11]
	v_add_u32_e32 v8, 32, v8
	v_mov_b32_e32 v20, 0
	v_mov_b32_e32 v21, 0
	v_mov_b32_e32 v22, 0
	v_mov_b32_e32 v23, 0
	v_cmp_gt_u32_e32 vcc, s46, v8
	s_and_saveexec_b64 s[10:11], vcc
	v_or_b32_e32 v6, s6, v8
	v_mov_b64_e32 v[4:5], s[22:23]
	v_mad_u64_u32 v[4:5], s[14:15], v6, s47, v[4:5]
	v_mad_i32_i24 v5, s7, v118, v5
	v_lshl_add_u64 v[4:5], s[4:5], 1, v[4:5]
	v_lshl_add_u64 v[4:5], v[4:5], 0, v[94:95]
	v_add_co_u32_e32 v4, vcc, 0xe402000, v4
	s_nop 1
	v_addc_co_u32_e32 v5, vcc, 0, v5, vcc
	global_load_dwordx4 v[20:23], v[4:5], off offset:1024
	s_or_b64 exec, exec, s[10:11]
	v_add_u32_e32 v8, 32, v8
	v_mov_b32_e32 v24, 0
	v_mov_b32_e32 v25, 0
	v_mov_b32_e32 v26, 0
	v_mov_b32_e32 v27, 0
	v_cmp_gt_u32_e32 vcc, s46, v8
	s_and_saveexec_b64 s[10:11], vcc
	v_or_b32_e32 v6, s6, v8
	v_mov_b64_e32 v[4:5], s[22:23]
	v_mad_u64_u32 v[4:5], s[14:15], v6, s47, v[4:5]
	v_mad_i32_i24 v5, s7, v118, v5
	v_lshl_add_u64 v[4:5], s[4:5], 1, v[4:5]
	v_lshl_add_u64 v[4:5], v[4:5], 0, v[94:95]
	v_add_co_u32_e32 v4, vcc, 0xe402000, v4
	s_nop 1
	v_addc_co_u32_e32 v5, vcc, 0, v5, vcc
	global_load_dwordx4 v[24:27], v[4:5], off offset:1024
	s_or_b64 exec, exec, s[10:11]
	v_add_u32_e32 v8, 32, v8
	v_mov_b32_e32 v28, 0
	v_mov_b32_e32 v29, 0
	v_mov_b32_e32 v30, 0
	v_mov_b32_e32 v31, 0
	v_cmp_gt_u32_e32 vcc, s46, v8
	s_and_saveexec_b64 s[10:11], vcc
	v_or_b32_e32 v6, s6, v8
	v_mov_b64_e32 v[4:5], s[22:23]
	v_mad_u64_u32 v[4:5], s[14:15], v6, s47, v[4:5]
	v_mad_i32_i24 v5, s7, v118, v5
	v_lshl_add_u64 v[4:5], s[4:5], 1, v[4:5]
	v_lshl_add_u64 v[4:5], v[4:5], 0, v[94:95]
	v_add_co_u32_e32 v4, vcc, 0xe402000, v4
	s_nop 1
	v_addc_co_u32_e32 v5, vcc, 0, v5, vcc
	global_load_dwordx4 v[28:31], v[4:5], off offset:1024
	s_or_b64 exec, exec, s[10:11]
	v_add_u32_e32 v8, 32, v8
	v_mov_b32_e32 v32, 0
	v_mov_b32_e32 v33, 0
	v_mov_b32_e32 v34, 0
	v_mov_b32_e32 v35, 0
	v_cmp_gt_u32_e32 vcc, s46, v8
	s_and_saveexec_b64 s[10:11], vcc
	v_or_b32_e32 v6, s6, v8
	v_mov_b64_e32 v[4:5], s[22:23]
	v_mad_u64_u32 v[4:5], s[14:15], v6, s47, v[4:5]
	v_mad_i32_i24 v5, s7, v118, v5
	v_lshl_add_u64 v[4:5], s[4:5], 1, v[4:5]
	v_lshl_add_u64 v[4:5], v[4:5], 0, v[94:95]
	v_add_co_u32_e32 v4, vcc, 0xe402000, v4
	s_nop 1
	v_addc_co_u32_e32 v5, vcc, 0, v5, vcc
	global_load_dwordx4 v[32:35], v[4:5], off offset:1024
	s_or_b64 exec, exec, s[10:11]
	v_add_u32_e32 v8, 32, v8
	v_mov_b32_e32 v36, 0
	v_mov_b32_e32 v37, 0
	v_mov_b32_e32 v38, 0
	v_mov_b32_e32 v39, 0
	v_cmp_gt_u32_e32 vcc, s46, v8
	s_and_saveexec_b64 s[10:11], vcc
	v_or_b32_e32 v6, s6, v8
	v_mov_b64_e32 v[4:5], s[22:23]
	v_mad_u64_u32 v[4:5], s[14:15], v6, s47, v[4:5]
	v_mad_i32_i24 v5, s7, v118, v5
	v_lshl_add_u64 v[4:5], s[4:5], 1, v[4:5]
	v_lshl_add_u64 v[4:5], v[4:5], 0, v[94:95]
	v_add_co_u32_e32 v4, vcc, 0xe402000, v4
	s_nop 1
	v_addc_co_u32_e32 v5, vcc, 0, v5, vcc
	global_load_dwordx4 v[36:39], v[4:5], off offset:1024
	s_or_b64 exec, exec, s[10:11]
	v_add_u32_e32 v8, 32, v8
	v_mov_b32_e32 v40, 0
	v_mov_b32_e32 v41, 0
	v_mov_b32_e32 v42, 0
	v_mov_b32_e32 v43, 0
	v_cmp_gt_u32_e32 vcc, s46, v8
	s_and_saveexec_b64 s[10:11], vcc
	v_or_b32_e32 v6, s6, v8
	v_mov_b64_e32 v[4:5], s[22:23]
	v_mad_u64_u32 v[4:5], s[14:15], v6, s47, v[4:5]
	v_mad_i32_i24 v5, s7, v118, v5
	v_lshl_add_u64 v[4:5], s[4:5], 1, v[4:5]
	v_lshl_add_u64 v[4:5], v[4:5], 0, v[94:95]
	v_add_co_u32_e32 v4, vcc, 0xe402000, v4
	s_nop 1
	v_addc_co_u32_e32 v5, vcc, 0, v5, vcc
	global_load_dwordx4 v[40:43], v[4:5], off offset:1024
	s_or_b64 exec, exec, s[10:11]
	s_waitcnt vmcnt(6)
	v_add_u32_e32 v10, 0x2200, v113
	s_and_saveexec_b64 s[10:11], s[8:9]
	s_cbranch_execz .Lstg_p1a_w8
	ds_write_b128 v10, v[44:47] offset:60928
; #define LAS __attribute__((address_space(3)))
; template <bool PASS2>
; __device__ __forceinline__ void lru_item(const Frame& F, const Args& a, int item) {
;     ...
;     for (int idx = F.tid; idx < 259 * 16; idx += 512) { const int row = idx >> 4, ch = idx & 15; const int t = t0 - 1 + row; u32x4 v = (u32x4){0u, 0u, 0u, 0u};
;         if (t >= 0 && t < SEQ) v = *(const u32x4*)(proj + (rowbase + t) * NIN + C_XB + n * 128 + 8 * ch);
;         *(LAS u32x4*)(R0 + row * AT_PITCH + 16 * ch) = v; }
;     {
;         f32x4 cw[4][2], cbv[2];
; #pragma unroll
;         for (int j = 0; j < 4; ++j) { cw[j][0] = *(const f32x4*)(a.conv_w + j * 1536 + n * 128 + 8 * cch); cw[j][1] = *(const f32x4*)(a.conv_w + j * 1536 + n * 128 + 8 * cch + 4); }
;         cbv[0] = *(const f32x4*)(a.conv_b + n * 128 + 8 * cch); cbv[1] = *(const f32x4*)(a.conv_b + n * 128 + 8 * cch + 4);
;         u32x4 ybv[8];
;         if (PASS2) {
; #pragma unroll
;             for (int it = 0; it < 8; ++it) ybv[it] = *(const u32x4*)(proj + (rowbase + t0 + r0 + 32 * it) * NIN + C_YB + n * 128 + 8 * cch);
;         }
;         __syncthreads();
.Lstg_p1a_w8:
	s_or_b64 exec, exec, s[10:11]
	ds_write_b128 v113, v[12:15]
	ds_write_b128 v113, v[16:19] offset:8704
	s_waitcnt vmcnt(5)
	ds_write_b128 v113, v[20:23] offset:17408
	s_waitcnt vmcnt(4)
	ds_write_b128 v113, v[24:27] offset:26112
	s_waitcnt vmcnt(3)
	ds_write_b128 v113, v[28:31] offset:34816
	s_waitcnt vmcnt(2)
	ds_write_b128 v113, v[32:35] offset:43520
	s_waitcnt vmcnt(1)
	ds_write_b128 v113, v[36:39] offset:52224
	s_waitcnt vmcnt(0)
	ds_write_b128 v113, v[40:43] offset:60928
	s_lshl_b64 s[6:7], s[4:5], 2
	v_lshl_add_u64 v[16:17], v[96:97], 0, s[6:7]
	v_add_co_u32_e32 v4, vcc, 0x1000, v16
	v_lshl_add_u64 v[8:9], v[16:17], 0, s[30:31]
	s_nop 0
	v_addc_co_u32_e32 v5, vcc, 0, v17, vcc
	v_add_co_u32_e32 v14, vcc, 0x3000, v16
	v_lshl_add_u64 v[12:13], v[16:17], 0, s[34:35]
	s_nop 0
	v_addc_co_u32_e32 v15, vcc, 0, v17, vcc
	global_load_dwordx4 v[36:39], v[16:17], off
	global_load_dwordx4 v[32:35], v[16:17], off offset:16
	s_nop 0
	global_load_dwordx4 v[4:7], v[4:5], off offset:2048
	s_nop 0
	global_load_dwordx4 v[8:11], v[8:9], off offset:16
	s_nop 0
	global_load_dwordx4 v[46:49], v[14:15], off
	global_load_dwordx4 v[40:43], v[12:13], off offset:16
	v_lshl_add_u64 v[12:13], v[16:17], 0, s[36:37]
	v_add_co_u32_e32 v16, vcc, 0x4000, v16
	global_load_dwordx4 v[12:15], v[12:13], off offset:16
	s_nop 0
	v_addc_co_u32_e32 v17, vcc, 0, v17, vcc
	global_load_dwordx4 v[16:19], v[16:17], off offset:2048
	v_lshl_add_u64 v[24:25], v[98:99], 0, s[6:7]
	global_load_dwordx4 v[20:23], v[24:25], off
	s_nop 0
	global_load_dwordx4 v[24:27], v[24:25], off offset:16
	s_mov_b32 s5, 0
	v_mov_b32_e32 v44, v115
	v_mov_b32_e32 v45, v108
	s_waitcnt lgkmcnt(0)
	s_barrier
	s_waitcnt vmcnt(8)
	v_mov_b32_e32 v28, v34
	v_mov_b32_e32 v30, v32
	v_mov_b32_e32 v32, v38
	v_mov_b32_e32 v34, v36
	s_waitcnt vmcnt(6)
	v_mov_b32_e32 v29, v10
	v_mov_b32_e32 v10, v35
	v_mov_b32_e32 v31, v8
	v_mov_b32_e32 v8, v33
	v_mov_b32_e32 v33, v6
	v_mov_b32_e32 v6, v39
	v_mov_b32_e32 v35, v4
	v_mov_b32_e32 v4, v37
	s_waitcnt vmcnt(4)
	v_mov_b32_e32 v36, v42
	v_mov_b32_e32 v38, v40
	v_mov_b32_e32 v40, v48
	v_mov_b32_e32 v42, v46
	s_waitcnt vmcnt(3)
	v_mov_b32_e32 v37, v14
	v_mov_b32_e32 v14, v43
	v_mov_b32_e32 v39, v12
	v_mov_b32_e32 v12, v41
	s_waitcnt vmcnt(2)
	v_mov_b32_e32 v41, v18
	v_mov_b32_e32 v18, v49
	v_mov_b32_e32 v43, v16
	v_mov_b32_e32 v16, v47

; #define LAS __attribute__((address_space(3)))
; template <bool PASS2>
; __device__ __forceinline__ void lru_item(const Frame& F, const Args& a, int item) {
;     ...
;     for (int idx = F.tid; idx < 259 * 16; idx += 512) { const int row = idx >> 4, ch = idx & 15; const int t = t0 - 1 + row; u32x4 v = (u32x4){0u, 0u, 0u, 0u};
;         if (t >= 0 && t < SEQ) v = *(const u32x4*)(proj + (rowbase + t) * NIN + C_XB + n * 128 + 8 * ch);
;         *(LAS u32x4*)(R0 + row * AT_PITCH + 16 * ch) = v; }
.LBB0_699:
	s_mul_hi_i32 s2, s73, 0x2aaaaaab
	s_ashr_i32 s3, s2, 1
	s_lshr_b32 s8, s2, 31
	s_add_i32 s3, s3, s8
	s_mul_i32 s9, s3, 12
	s_sub_i32 s14, s73, s9
	s_ashr_i32 s9, s3, 31
	s_lshr_b32 s9, s9, 28
	s_add_i32 s9, s3, s9
	s_and_b32 s9, s9, -16
	s_ashr_i32 s2, s2, 5
	s_sub_i32 s33, s3, s9
	s_add_i32 s2, s2, s8
	s_lshl_b32 s74, s33, 8
	s_ashr_i32 s3, s2, 31
	s_lshl_b32 s44, s14, 7
	s_lshl_b64 s[8:9], s[2:3], 12
	s_ashr_i32 s45, s44, 31
	v_add_u32_e32 v8, s74, v111
	s_mov_b64 s[10:11], 0
	v_mov_b32_e32 v9, v115
	v_mov_b32_e32 v10, v113
	s_waitcnt vmcnt(0)
	s_barrier
	v_cmp_gt_u32_e64 s[10:11], 48, v144
	s_movk_i32 s3, 0x1000
	v_add_u32_e32 v9, 0x100, v8
	v_mov_b32_e32 v44, 0
	v_mov_b32_e32 v45, 0
	v_mov_b32_e32 v46, 0
	v_mov_b32_e32 v47, 0
	v_cmp_gt_u32_e32 vcc, s3, v9
	s_and_b64 vcc, vcc, s[10:11]
	s_and_saveexec_b64 s[12:13], vcc
	s_cbranch_execz .Lstg_p2a_8
	v_or_b32_e32 v6, s8, v9
	v_mov_b64_e32 v[4:5], s[34:35]
	v_mad_u64_u32 v[4:5], s[30:31], v6, s55, v[4:5]
	v_mad_i32_i24 v5, s9, v135, v5
	v_lshl_add_u64 v[4:5], s[44:45], 1, v[4:5]
	v_lshl_add_u64 v[4:5], v[4:5], 0, v[96:97]
	v_add_co_u32_e32 v4, vcc, 0x2000, v4
	s_nop 1
	v_addc_co_u32_e32 v5, vcc, 0, v5, vcc
	global_load_dwordx4 v[44:47], v[4:5], off offset:1024
.Lstg_p2a_8:
	s_or_b64 exec, exec, s[12:13]
	v_mov_b32_e32 v12, 0
	v_mov_b32_e32 v13, 0
	v_mov_b32_e32 v14, 0
	v_mov_b32_e32 v15, 0
	v_cmp_gt_u32_e32 vcc, s3, v8
	s_and_saveexec_b64 s[12:13], vcc
	s_cbranch_execz .Lstg_p2a_0
	v_or_b32_e32 v6, s8, v8
	v_mov_b64_e32 v[4:5], s[34:35]
	v_mad_u64_u32 v[4:5], s[30:31], v6, s55, v[4:5]
	v_mad_i32_i24 v5, s9, v135, v5
	v_lshl_add_u64 v[4:5], s[44:45], 1, v[4:5]
	v_lshl_add_u64 v[4:5], v[4:5], 0, v[96:97]
	v_add_co_u32_e32 v4, vcc, 0x2000, v4
	s_nop 1
	v_addc_co_u32_e32 v5, vcc, 0, v5, vcc
	global_load_dwordx4 v[12:15], v[4:5], off offset:1024
.Lstg_p2a_0:
	s_or_b64 exec, exec, s[12:13]
	v_add_u32_e32 v8, 32, v8
	v_mov_b32_e32 v16, 0
	v_mov_b32_e32 v17, 0
	v_mov_b32_e32 v18, 0
	v_mov_b32_e32 v19, 0
	v_cmp_gt_u32_e32 vcc, s3, v8
	s_and_saveexec_b64 s[12:13], vcc
	v_or_b32_e32 v6, s8, v8
	v_mov_b64_e32 v[4:5], s[34:35]
	v_mad_u64_u32 v[4:5], s[30:31], v6, s55, v[4:5]
	v_mad_i32_i24 v5, s9, v135, v5
	v_lshl_add_u64 v[4:5], s[44:45], 1, v[4:5]
	v_lshl_add_u64 v[4:5], v[4:5], 0, v[96:97]
	v_add_co_u32_e32 v4, vcc, 0x2000, v4
	s_nop 1
	v_addc_co_u32_e32 v5, vcc, 0, v5, vcc
	global_load_dwordx4 v[16:19], v[4:5], off offset:1024
	s_or_b64 exec, exec, s[12:13]
	v_add_u32_e32 v8, 32, v8
	v_mov_b32_e32 v20, 0
	v_mov_b32_e32 v21, 0
	v_mov_b32_e32 v22, 0
	v_mov_b32_e32 v23, 0
	v_cmp_gt_u32_e32 vcc, s3, v8
	s_and_saveexec_b64 s[12:13], vcc
	v_or_b32_e32 v6, s8, v8
	v_mov_b64_e32 v[4:5], s[34:35]
	v_mad_u64_u32 v[4:5], s[30:31], v6, s55, v[4:5]
	v_mad_i32_i24 v5, s9, v135, v5
	v_lshl_add_u64 v[4:5], s[44:45], 1, v[4:5]
	v_lshl_add_u64 v[4:5], v[4:5], 0, v[96:97]
	v_add_co_u32_e32 v4, vcc, 0x2000, v4
	s_nop 1
	v_addc_co_u32_e32 v5, vcc, 0, v5, vcc
	global_load_dwordx4 v[20:23], v[4:5], off offset:1024
	s_or_b64 exec, exec, s[12:13]
	v_add_u32_e32 v8, 32, v8
	v_mov_b32_e32 v24, 0
	v_mov_b32_e32 v25, 0
	v_mov_b32_e32 v26, 0
	v_mov_b32_e32 v27, 0
	v_cmp_gt_u32_e32 vcc, s3, v8
	s_and_saveexec_b64 s[12:13], vcc
	v_or_b32_e32 v6, s8, v8
	v_mov_b64_e32 v[4:5], s[34:35]
	v_mad_u64_u32 v[4:5], s[30:31], v6, s55, v[4:5]
	v_mad_i32_i24 v5, s9, v135, v5
	v_lshl_add_u64 v[4:5], s[44:45], 1, v[4:5]
	v_lshl_add_u64 v[4:5], v[4:5], 0, v[96:97]
	v_add_co_u32_e32 v4, vcc, 0x2000, v4
	s_nop 1
	v_addc_co_u32_e32 v5, vcc, 0, v5, vcc
	global_load_dwordx4 v[24:27], v[4:5], off offset:1024
	s_or_b64 exec, exec, s[12:13]
	v_add_u32_e32 v8, 32, v8
	v_mov_b32_e32 v28, 0
	v_mov_b32_e32 v29, 0
	v_mov_b32_e32 v30, 0
	v_mov_b32_e32 v31, 0
	v_cmp_gt_u32_e32 vcc, s3, v8
	s_and_saveexec_b64 s[12:13], vcc
	v_or_b32_e32 v6, s8, v8
	v_mov_b64_e32 v[4:5], s[34:35]
	v_mad_u64_u32 v[4:5], s[30:31], v6, s55, v[4:5]
	v_mad_i32_i24 v5, s9, v135, v5
	v_lshl_add_u64 v[4:5], s[44:45], 1, v[4:5]
	v_lshl_add_u64 v[4:5], v[4:5], 0, v[96:97]
	v_add_co_u32_e32 v4, vcc, 0x2000, v4
	s_nop 1
	v_addc_co_u32_e32 v5, vcc, 0, v5, vcc
	global_load_dwordx4 v[28:31], v[4:5], off offset:1024
	s_or_b64 exec, exec, s[12:13]
	v_add_u32_e32 v8, 32, v8
	v_mov_b32_e32 v32, 0
	v_mov_b32_e32 v33, 0
	v_mov_b32_e32 v34, 0
	v_mov_b32_e32 v35, 0
	v_cmp_gt_u32_e32 vcc, s3, v8
	s_and_saveexec_b64 s[12:13], vcc
	v_or_b32_e32 v6, s8, v8
	v_mov_b64_e32 v[4:5], s[34:35]
	v_mad_u64_u32 v[4:5], s[30:31], v6, s55, v[4:5]
	v_mad_i32_i24 v5, s9, v135, v5
	v_lshl_add_u64 v[4:5], s[44:45], 1, v[4:5]
	v_lshl_add_u64 v[4:5], v[4:5], 0, v[96:97]
	v_add_co_u32_e32 v4, vcc, 0x2000, v4
	s_nop 1
	v_addc_co_u32_e32 v5, vcc, 0, v5, vcc
	global_load_dwordx4 v[32:35], v[4:5], off offset:1024
	s_or_b64 exec, exec, s[12:13]
	v_add_u32_e32 v8, 32, v8
	v_mov_b32_e32 v36, 0
	v_mov_b32_e32 v37, 0
	v_mov_b32_e32 v38, 0
	v_mov_b32_e32 v39, 0
	v_cmp_gt_u32_e32 vcc, s3, v8
	s_and_saveexec_b64 s[12:13], vcc
	v_or_b32_e32 v6, s8, v8
	v_mov_b64_e32 v[4:5], s[34:35]
	v_mad_u64_u32 v[4:5], s[30:31], v6, s55, v[4:5]
	v_mad_i32_i24 v5, s9, v135, v5
	v_lshl_add_u64 v[4:5], s[44:45], 1, v[4:5]
	v_lshl_add_u64 v[4:5], v[4:5], 0, v[96:97]
	v_add_co_u32_e32 v4, vcc, 0x2000, v4
	s_nop 1
	v_addc_co_u32_e32 v5, vcc, 0, v5, vcc
	global_load_dwordx4 v[36:39], v[4:5], off offset:1024
	s_or_b64 exec, exec, s[12:13]
	v_add_u32_e32 v8, 32, v8
	v_mov_b32_e32 v40, 0
	v_mov_b32_e32 v41, 0
	v_mov_b32_e32 v42, 0
	v_mov_b32_e32 v43, 0
	v_cmp_gt_u32_e32 vcc, s3, v8
	s_and_saveexec_b64 s[12:13], vcc
	v_or_b32_e32 v6, s8, v8
	v_mov_b64_e32 v[4:5], s[34:35]
	v_mad_u64_u32 v[4:5], s[30:31], v6, s55, v[4:5]
	v_mad_i32_i24 v5, s9, v135, v5
	v_lshl_add_u64 v[4:5], s[44:45], 1, v[4:5]
	v_lshl_add_u64 v[4:5], v[4:5], 0, v[96:97]
	v_add_co_u32_e32 v4, vcc, 0x2000, v4
	s_nop 1
	v_addc_co_u32_e32 v5, vcc, 0, v5, vcc
	global_load_dwordx4 v[40:43], v[4:5], off offset:1024
	s_or_b64 exec, exec, s[12:13]
	s_waitcnt vmcnt(6)
	v_add_u32_e32 v10, 0x2200, v113
	s_and_saveexec_b64 s[12:13], s[10:11]
	s_cbranch_execz .Lstg_p2a_w8
	ds_write_b128 v10, v[44:47] offset:60928
; #define LAS __attribute__((address_space(3)))
; template <bool PASS2>
; __device__ __forceinline__ void lru_item(const Frame& F, const Args& a, int item) {
;     ...
;     for (int idx = F.tid; idx < 259 * 16; idx += 512) { const int row = idx >> 4, ch = idx & 15; const int t = t0 - 1 + row; u32x4 v = (u32x4){0u, 0u, 0u, 0u};
;         if (t >= 0 && t < SEQ) v = *(const u32x4*)(proj + (rowbase + t) * NIN + C_XB + n * 128 + 8 * ch);
;         *(LAS u32x4*)(R0 + row * AT_PITCH + 16 * ch) = v; }
;     {
;         f32x4 cw[4][2], cbv[2];
; #pragma unroll
;         for (int j = 0; j < 4; ++j) { cw[j][0] = *(const f32x4*)(a.conv_w + j * 1536 + n * 128 + 8 * cch); cw[j][1] = *(const f32x4*)(a.conv_w + j * 1536 + n * 128 + 8 * cch + 4); }
;         cbv[0] = *(const f32x4*)(a.conv_b + n * 128 + 8 * cch); cbv[1] = *(const f32x4*)(a.conv_b + n * 128 + 8 * cch + 4);
;         u32x4 ybv[8];
;         if (PASS2) {
; #pragma unroll
;             for (int it = 0; it < 8; ++it) ybv[it] = *(const u32x4*)(proj + (rowbase + t0 + r0 + 32 * it) * NIN + C_YB + n * 128 + 8 * cch);
;         }
;         __syncthreads();
.Lstg_p2a_w8:
	s_or_b64 exec, exec, s[12:13]
	ds_write_b128 v113, v[12:15]
	ds_write_b128 v113, v[16:19] offset:8704
	s_waitcnt vmcnt(5)
	ds_write_b128 v113, v[20:23] offset:17408
	s_waitcnt vmcnt(4)
	ds_write_b128 v113, v[24:27] offset:26112
	s_waitcnt vmcnt(3)
	ds_write_b128 v113, v[28:31] offset:34816
	s_waitcnt vmcnt(2)
	ds_write_b128 v113, v[32:35] offset:43520
	s_waitcnt vmcnt(1)
	ds_write_b128 v113, v[36:39] offset:52224
	s_waitcnt vmcnt(0)
	ds_write_b128 v113, v[40:43] offset:60928
	s_lshl_b64 s[10:11], s[44:45], 2
	v_lshl_add_u64 v[4:5], v[98:99], 0, s[10:11]
	v_add_co_u32_e32 v8, vcc, 0x1000, v4
	s_mov_b64 s[12:13], 0x1800
	s_nop 0
	v_addc_co_u32_e32 v9, vcc, 0, v5, vcc
	global_load_dwordx4 v[76:79], v[4:5], off
	global_load_dwordx4 v[68:71], v[4:5], off offset:16
	v_lshl_add_u64 v[6:7], v[4:5], 0, s[12:13]
	global_load_dwordx4 v[36:39], v[8:9], off offset:2048
	global_load_dwordx4 v[40:43], v[6:7], off offset:16
	s_mov_b64 s[12:13], 0x3000
	v_add_co_u32_e32 v8, vcc, 0x3000, v4
	v_lshl_add_u64 v[6:7], v[4:5], 0, s[12:13]
	s_nop 0
	v_addc_co_u32_e32 v9, vcc, 0, v5, vcc
	s_mov_b64 s[12:13], 0x4800
	global_load_dwordx4 v[80:83], v[8:9], off
	global_load_dwordx4 v[72:75], v[6:7], off offset:16
	v_lshl_add_u64 v[6:7], v[4:5], 0, s[12:13]
	v_add_co_u32_e32 v4, vcc, 0x4000, v4
	s_ashr_i32 s3, s74, 31
	s_nop 0
	v_addc_co_u32_e32 v5, vcc, 0, v5, vcc
	global_load_dwordx4 v[44:47], v[4:5], off offset:2048
	global_load_dwordx4 v[48:51], v[6:7], off offset:16
	v_lshl_add_u64 v[4:5], v[100:101], 0, s[10:11]
	s_add_u32 s46, s8, s74
	global_load_dwordx4 v[52:55], v[4:5], off
	global_load_dwordx4 v[56:59], v[4:5], off offset:16
	v_or_b32_e32 v122, s46, v94
	v_mov_b64_e32 v[4:5], s[34:35]
	s_addc_u32 s47, s9, s3
	v_mad_u64_u32 v[4:5], s[8:9], v122, s55, v[4:5]
	v_mad_i32_i24 v5, s47, v135, v5
	v_lshl_add_u64 v[4:5], s[44:45], 1, v[4:5]
	v_lshl_add_u64 v[28:29], v[4:5], 0, v[96:97]
	s_movk_i32 s3, 0x3000
	v_add_co_u32_e32 v4, vcc, s3, v28
	s_mov_b32 s3, 0x8b000
	s_nop 0
	v_addc_co_u32_e32 v5, vcc, 0, v29, vcc
	v_add_co_u32_e32 v8, vcc, s3, v28
	s_mov_b32 s3, 0x113000
	s_nop 0
	v_addc_co_u32_e32 v9, vcc, 0, v29, vcc
	v_add_co_u32_e32 v12, vcc, s3, v28
	s_mov_b32 s3, 0x19b000
	s_nop 0
	v_addc_co_u32_e32 v13, vcc, 0, v29, vcc
	v_add_co_u32_e32 v16, vcc, s3, v28
	s_mov_b32 s3, 0x223000
	s_nop 0
	v_addc_co_u32_e32 v17, vcc, 0, v29, vcc
	v_add_co_u32_e32 v20, vcc, s3, v28
	s_mov_b32 s3, 0x2ab000
	s_nop 0
	v_addc_co_u32_e32 v21, vcc, 0, v29, vcc
	v_add_co_u32_e32 v24, vcc, s3, v28
	s_mov_b32 s3, 0x333000
	s_nop 0
	v_addc_co_u32_e32 v25, vcc, 0, v29, vcc
	v_add_co_u32_e32 v30, vcc, s3, v28
	s_mov_b32 s3, 0x3bb000
	s_nop 0
	v_addc_co_u32_e32 v31, vcc, 0, v29, vcc
	v_add_co_u32_e32 v32, vcc, s3, v28
	global_load_dwordx4 v[4:7], v[4:5], off
	s_nop 0
	global_load_dwordx4 v[8:11], v[8:9], off
	v_addc_co_u32_e32 v33, vcc, 0, v29, vcc
	global_load_dwordx4 v[12:15], v[12:13], off
	s_nop 0
	global_load_dwordx4 v[16:19], v[16:17], off
	s_nop 0
	global_load_dwordx4 v[20:23], v[20:21], off
	s_nop 0
	global_load_dwordx4 v[24:27], v[24:25], off
	s_nop 0
	global_load_dwordx4 v[28:31], v[30:31], off
	s_nop 0
	global_load_dwordx4 v[32:35], v[32:33], off
	s_mov_b32 s3, 0
	v_mov_b32_e32 v93, s47
	s_waitcnt lgkmcnt(0)
	s_barrier
	s_waitcnt vmcnt(16)
	v_mov_b32_e32 v62, v70
	v_mov_b32_e32 v66, v68
	s_waitcnt vmcnt(14)
	v_mov_b32_e32 v63, v42
	v_mov_b32_e32 v42, v71
	v_mov_b32_e32 v67, v40
	v_mov_b32_e32 v40, v69
	v_mov_b32_e32 v70, v78
	v_mov_b32_e32 v71, v38
	v_mov_b32_e32 v38, v79
	s_waitcnt vmcnt(13)
	v_mov_b32_e32 v68, v82
	s_waitcnt vmcnt(12)
	v_mov_b32_e32 v60, v74
	v_mov_b32_e32 v64, v72
	v_mov_b32_e32 v72, v80
	v_mov_b32_e32 v74, v76
	v_mov_b32_e32 v76, v121
	s_waitcnt vmcnt(11)
	v_mov_b32_e32 v69, v46
	s_waitcnt vmcnt(10)
	v_mov_b32_e32 v61, v50
	v_mov_b32_e32 v50, v75
	v_mov_b32_e32 v65, v48
	v_mov_b32_e32 v48, v73
	v_mov_b32_e32 v46, v83
	v_mov_b32_e32 v73, v44
	v_mov_b32_e32 v44, v81
	v_mov_b32_e32 v75, v36
	v_mov_b32_e32 v36, v77
	v_mov_b32_e32 v77, v94

; #define LAS __attribute__((address_space(3)))
; template <bool PASS2>
; __device__ __forceinline__ void lru_item(const Frame& F, const Args& a, int item) {
;     ...
;     for (int idx = F.tid; idx < 259 * 16; idx += 512) { const int row = idx >> 4, ch = idx & 15; const int t = t0 - 1 + row; u32x4 v = (u32x4){0u, 0u, 0u, 0u};
;         if (t >= 0 && t < SEQ) v = *(const u32x4*)(proj + (rowbase + t) * NIN + C_XB + n * 128 + 8 * ch);
;         *(LAS u32x4*)(R0 + row * AT_PITCH + 16 * ch) = v; }
.LBB0_818:
	s_mul_hi_i32 s8, s78, 0x2aaaaaab
	s_ashr_i32 s9, s8, 1
	s_lshr_b32 s10, s8, 31
	s_add_i32 s9, s9, s10
	s_mul_i32 s11, s9, 12
	s_sub_i32 s29, s78, s11
	s_ashr_i32 s11, s9, 31
	s_lshr_b32 s11, s11, 28
	s_add_i32 s11, s9, s11
	s_and_b32 s11, s11, -16
	s_ashr_i32 s8, s8, 5
	s_sub_i32 s80, s9, s11
	s_add_i32 s8, s8, s10
	s_lshl_b32 s79, s80, 8
	s_ashr_i32 s9, s8, 31
	s_lshl_b32 s42, s29, 7
	s_lshl_b64 s[10:11], s[8:9], 12
	s_ashr_i32 s43, s42, 31
	v_add_u32_e32 v8, s79, v109
	s_mov_b64 s[12:13], 0
	v_mov_b32_e32 v9, v113
	v_mov_b32_e32 v10, v111
	s_barrier
	v_cmp_gt_u32_e64 s[12:13], 48, v144
	s_movk_i32 s9, 0x1000
	v_add_u32_e32 v9, 0x100, v8
	v_mov_b32_e32 v44, 0
	v_mov_b32_e32 v45, 0
	v_mov_b32_e32 v46, 0
	v_mov_b32_e32 v47, 0
	v_cmp_gt_u32_e32 vcc, s9, v9
	s_and_b64 vcc, vcc, s[12:13]
	s_and_saveexec_b64 s[14:15], vcc
	s_cbranch_execz .Lstg_p2b_8
	v_or_b32_e32 v6, s10, v9
	v_mov_b64_e32 v[4:5], s[34:35]
	v_mad_u64_u32 v[4:5], s[30:31], v6, s52, v[4:5]
	v_mad_i32_i24 v5, s11, v134, v5
	v_lshl_add_u64 v[4:5], s[42:43], 1, v[4:5]
	v_lshl_add_u64 v[4:5], v[4:5], 0, v[96:97]
	v_add_co_u32_e32 v4, vcc, 0x2000, v4
	s_nop 1
	v_addc_co_u32_e32 v5, vcc, 0, v5, vcc
	global_load_dwordx4 v[44:47], v[4:5], off offset:1024
.Lstg_p2b_8:
	s_or_b64 exec, exec, s[14:15]
	v_mov_b32_e32 v12, 0
	v_mov_b32_e32 v13, 0
	v_mov_b32_e32 v14, 0
	v_mov_b32_e32 v15, 0
	v_cmp_gt_u32_e32 vcc, s9, v8
	s_and_saveexec_b64 s[14:15], vcc
	s_cbranch_execz .Lstg_p2b_0
	v_or_b32_e32 v6, s10, v8
	v_mov_b64_e32 v[4:5], s[34:35]
	v_mad_u64_u32 v[4:5], s[30:31], v6, s52, v[4:5]
	v_mad_i32_i24 v5, s11, v134, v5
	v_lshl_add_u64 v[4:5], s[42:43], 1, v[4:5]
	v_lshl_add_u64 v[4:5], v[4:5], 0, v[96:97]
	v_add_co_u32_e32 v4, vcc, 0x2000, v4
	s_nop 1
	v_addc_co_u32_e32 v5, vcc, 0, v5, vcc
	global_load_dwordx4 v[12:15], v[4:5], off offset:1024
.Lstg_p2b_0:
	s_or_b64 exec, exec, s[14:15]
	v_add_u32_e32 v8, 32, v8
	v_mov_b32_e32 v16, 0
	v_mov_b32_e32 v17, 0
	v_mov_b32_e32 v18, 0
	v_mov_b32_e32 v19, 0
	v_cmp_gt_u32_e32 vcc, s9, v8
	s_and_saveexec_b64 s[14:15], vcc
	v_or_b32_e32 v6, s10, v8
	v_mov_b64_e32 v[4:5], s[34:35]
	v_mad_u64_u32 v[4:5], s[30:31], v6, s52, v[4:5]
	v_mad_i32_i24 v5, s11, v134, v5
	v_lshl_add_u64 v[4:5], s[42:43], 1, v[4:5]
	v_lshl_add_u64 v[4:5], v[4:5], 0, v[96:97]
	v_add_co_u32_e32 v4, vcc, 0x2000, v4
	s_nop 1
	v_addc_co_u32_e32 v5, vcc, 0, v5, vcc
	global_load_dwordx4 v[16:19], v[4:5], off offset:1024
	s_or_b64 exec, exec, s[14:15]
	v_add_u32_e32 v8, 32, v8
	v_mov_b32_e32 v20, 0
	v_mov_b32_e32 v21, 0
	v_mov_b32_e32 v22, 0
	v_mov_b32_e32 v23, 0
	v_cmp_gt_u32_e32 vcc, s9, v8
	s_and_saveexec_b64 s[14:15], vcc
	v_or_b32_e32 v6, s10, v8
	v_mov_b64_e32 v[4:5], s[34:35]
	v_mad_u64_u32 v[4:5], s[30:31], v6, s52, v[4:5]
	v_mad_i32_i24 v5, s11, v134, v5
	v_lshl_add_u64 v[4:5], s[42:43], 1, v[4:5]
	v_lshl_add_u64 v[4:5], v[4:5], 0, v[96:97]
	v_add_co_u32_e32 v4, vcc, 0x2000, v4
	s_nop 1
	v_addc_co_u32_e32 v5, vcc, 0, v5, vcc
	global_load_dwordx4 v[20:23], v[4:5], off offset:1024
	s_or_b64 exec, exec, s[14:15]
	v_add_u32_e32 v8, 32, v8
	v_mov_b32_e32 v24, 0
	v_mov_b32_e32 v25, 0
	v_mov_b32_e32 v26, 0
	v_mov_b32_e32 v27, 0
	v_cmp_gt_u32_e32 vcc, s9, v8
	s_and_saveexec_b64 s[14:15], vcc
	v_or_b32_e32 v6, s10, v8
	v_mov_b64_e32 v[4:5], s[34:35]
	v_mad_u64_u32 v[4:5], s[30:31], v6, s52, v[4:5]
	v_mad_i32_i24 v5, s11, v134, v5
	v_lshl_add_u64 v[4:5], s[42:43], 1, v[4:5]
	v_lshl_add_u64 v[4:5], v[4:5], 0, v[96:97]
	v_add_co_u32_e32 v4, vcc, 0x2000, v4
	s_nop 1
	v_addc_co_u32_e32 v5, vcc, 0, v5, vcc
	global_load_dwordx4 v[24:27], v[4:5], off offset:1024
	s_or_b64 exec, exec, s[14:15]
	v_add_u32_e32 v8, 32, v8
	v_mov_b32_e32 v28, 0
	v_mov_b32_e32 v29, 0
	v_mov_b32_e32 v30, 0
	v_mov_b32_e32 v31, 0
	v_cmp_gt_u32_e32 vcc, s9, v8
	s_and_saveexec_b64 s[14:15], vcc
	v_or_b32_e32 v6, s10, v8
	v_mov_b64_e32 v[4:5], s[34:35]
	v_mad_u64_u32 v[4:5], s[30:31], v6, s52, v[4:5]
	v_mad_i32_i24 v5, s11, v134, v5
	v_lshl_add_u64 v[4:5], s[42:43], 1, v[4:5]
	v_lshl_add_u64 v[4:5], v[4:5], 0, v[96:97]
	v_add_co_u32_e32 v4, vcc, 0x2000, v4
	s_nop 1
	v_addc_co_u32_e32 v5, vcc, 0, v5, vcc
	global_load_dwordx4 v[28:31], v[4:5], off offset:1024
	s_or_b64 exec, exec, s[14:15]
	v_add_u32_e32 v8, 32, v8
	v_mov_b32_e32 v32, 0
	v_mov_b32_e32 v33, 0
	v_mov_b32_e32 v34, 0
	v_mov_b32_e32 v35, 0
	v_cmp_gt_u32_e32 vcc, s9, v8
	s_and_saveexec_b64 s[14:15], vcc
	v_or_b32_e32 v6, s10, v8
	v_mov_b64_e32 v[4:5], s[34:35]
	v_mad_u64_u32 v[4:5], s[30:31], v6, s52, v[4:5]
	v_mad_i32_i24 v5, s11, v134, v5
	v_lshl_add_u64 v[4:5], s[42:43], 1, v[4:5]
	v_lshl_add_u64 v[4:5], v[4:5], 0, v[96:97]
	v_add_co_u32_e32 v4, vcc, 0x2000, v4
	s_nop 1
	v_addc_co_u32_e32 v5, vcc, 0, v5, vcc
	global_load_dwordx4 v[32:35], v[4:5], off offset:1024
	s_or_b64 exec, exec, s[14:15]
	v_add_u32_e32 v8, 32, v8
	v_mov_b32_e32 v36, 0
	v_mov_b32_e32 v37, 0
	v_mov_b32_e32 v38, 0
	v_mov_b32_e32 v39, 0
	v_cmp_gt_u32_e32 vcc, s9, v8
	s_and_saveexec_b64 s[14:15], vcc
	v_or_b32_e32 v6, s10, v8
	v_mov_b64_e32 v[4:5], s[34:35]
	v_mad_u64_u32 v[4:5], s[30:31], v6, s52, v[4:5]
	v_mad_i32_i24 v5, s11, v134, v5
	v_lshl_add_u64 v[4:5], s[42:43], 1, v[4:5]
	v_lshl_add_u64 v[4:5], v[4:5], 0, v[96:97]
	v_add_co_u32_e32 v4, vcc, 0x2000, v4
	s_nop 1
	v_addc_co_u32_e32 v5, vcc, 0, v5, vcc
	global_load_dwordx4 v[36:39], v[4:5], off offset:1024
	s_or_b64 exec, exec, s[14:15]
	v_add_u32_e32 v8, 32, v8
	v_mov_b32_e32 v40, 0
	v_mov_b32_e32 v41, 0
	v_mov_b32_e32 v42, 0
	v_mov_b32_e32 v43, 0
	v_cmp_gt_u32_e32 vcc, s9, v8
	s_and_saveexec_b64 s[14:15], vcc
	v_or_b32_e32 v6, s10, v8
	v_mov_b64_e32 v[4:5], s[34:35]
	v_mad_u64_u32 v[4:5], s[30:31], v6, s52, v[4:5]
	v_mad_i32_i24 v5, s11, v134, v5
	v_lshl_add_u64 v[4:5], s[42:43], 1, v[4:5]
	v_lshl_add_u64 v[4:5], v[4:5], 0, v[96:97]
	v_add_co_u32_e32 v4, vcc, 0x2000, v4
	s_nop 1
	v_addc_co_u32_e32 v5, vcc, 0, v5, vcc
	global_load_dwordx4 v[40:43], v[4:5], off offset:1024
	s_or_b64 exec, exec, s[14:15]
	s_waitcnt vmcnt(6)
	v_add_u32_e32 v10, 0x2200, v111
	s_and_saveexec_b64 s[14:15], s[12:13]
	s_cbranch_execz .Lstg_p2b_w8
	ds_write_b128 v10, v[44:47] offset:60928
; #define LAS __attribute__((address_space(3)))
; template <bool PASS2>
; __device__ __forceinline__ void lru_item(const Frame& F, const Args& a, int item) {
;     ...
;     for (int idx = F.tid; idx < 259 * 16; idx += 512) { const int row = idx >> 4, ch = idx & 15; const int t = t0 - 1 + row; u32x4 v = (u32x4){0u, 0u, 0u, 0u};
;         if (t >= 0 && t < SEQ) v = *(const u32x4*)(proj + (rowbase + t) * NIN + C_XB + n * 128 + 8 * ch);
;         *(LAS u32x4*)(R0 + row * AT_PITCH + 16 * ch) = v; }
;     {
;         f32x4 cw[4][2], cbv[2];
; #pragma unroll
;         for (int j = 0; j < 4; ++j) { cw[j][0] = *(const f32x4*)(a.conv_w + j * 1536 + n * 128 + 8 * cch); cw[j][1] = *(const f32x4*)(a.conv_w + j * 1536 + n * 128 + 8 * cch + 4); }
;         cbv[0] = *(const f32x4*)(a.conv_b + n * 128 + 8 * cch); cbv[1] = *(const f32x4*)(a.conv_b + n * 128 + 8 * cch + 4);
;         u32x4 ybv[8];
;         if (PASS2) {
; #pragma unroll
;             for (int it = 0; it < 8; ++it) ybv[it] = *(const u32x4*)(proj + (rowbase + t0 + r0 + 32 * it) * NIN + C_YB + n * 128 + 8 * cch);
;         }
;         __syncthreads();
.Lstg_p2b_w8:
	s_or_b64 exec, exec, s[14:15]
	ds_write_b128 v111, v[12:15]
	ds_write_b128 v111, v[16:19] offset:8704
	s_waitcnt vmcnt(5)
	ds_write_b128 v111, v[20:23] offset:17408
	s_waitcnt vmcnt(4)
	ds_write_b128 v111, v[24:27] offset:26112
	s_waitcnt vmcnt(3)
	ds_write_b128 v111, v[28:31] offset:34816
	s_waitcnt vmcnt(2)
	ds_write_b128 v111, v[32:35] offset:43520
	s_waitcnt vmcnt(1)
	ds_write_b128 v111, v[36:39] offset:52224
	s_waitcnt vmcnt(0)
	ds_write_b128 v111, v[40:43] offset:60928
	s_lshl_b64 s[12:13], s[42:43], 2
	v_lshl_add_u64 v[12:13], v[98:99], 0, s[12:13]
	s_ashr_i32 s9, s79, 31
	v_add_co_u32_e32 v4, vcc, 0x1000, v12
	s_add_u32 s44, s10, s79
	s_mov_b64 s[14:15], 0x1800
	v_addc_co_u32_e32 v5, vcc, 0, v13, vcc
	v_or_b32_e32 v122, s44, v94
	v_mov_b64_e32 v[28:29], s[34:35]
	v_lshl_add_u64 v[8:9], v[12:13], 0, s[14:15]
	s_mov_b64 s[14:15], 0x3000
	v_add_co_u32_e32 v16, vcc, 0x3000, v12
	s_addc_u32 s45, s11, s9
	v_mad_u64_u32 v[28:29], s[10:11], v122, s52, v[28:29]
	v_lshl_add_u64 v[14:15], v[12:13], 0, s[14:15]
	v_addc_co_u32_e32 v17, vcc, 0, v13, vcc
	s_mov_b64 s[14:15], 0x4800
	v_mad_i32_i24 v29, s45, v134, v29
	global_load_dwordx4 v[76:79], v[12:13], off
	global_load_dwordx4 v[68:71], v[12:13], off offset:16
	s_nop 0
	global_load_dwordx4 v[4:7], v[4:5], off offset:2048
	s_nop 0
	global_load_dwordx4 v[8:11], v[8:9], off offset:16
	s_nop 0
	global_load_dwordx4 v[80:83], v[16:17], off
	global_load_dwordx4 v[72:75], v[14:15], off offset:16
	v_lshl_add_u64 v[16:17], v[12:13], 0, s[14:15]
	v_add_co_u32_e32 v12, vcc, 0x4000, v12
	v_lshl_add_u64 v[28:29], s[42:43], 1, v[28:29]
	s_nop 0
	v_addc_co_u32_e32 v13, vcc, 0, v13, vcc
	v_lshl_add_u64 v[28:29], v[28:29], 0, v[96:97]
	s_movk_i32 s9, 0x3000
	v_add_co_u32_e32 v30, vcc, s9, v28
	s_mov_b32 s9, 0x8b000
	s_nop 0
	v_addc_co_u32_e32 v31, vcc, 0, v29, vcc
	v_add_co_u32_e32 v32, vcc, s9, v28
	v_lshl_add_u64 v[24:25], v[100:101], 0, s[12:13]
	s_nop 0
	v_addc_co_u32_e32 v33, vcc, 0, v29, vcc
	s_mov_b32 s9, 0x113000
	global_load_dwordx4 v[12:15], v[12:13], off offset:2048
	s_nop 0
	global_load_dwordx4 v[16:19], v[16:17], off offset:16
	s_nop 0
	global_load_dwordx4 v[20:23], v[24:25], off
	s_nop 0
	global_load_dwordx4 v[24:27], v[24:25], off offset:16
	s_nop 0
	global_load_dwordx4 v[36:39], v[30:31], off
	global_load_dwordx4 v[40:43], v[32:33], off
	v_add_co_u32_e32 v30, vcc, s9, v28
	s_mov_b32 s9, 0x19b000
	s_nop 0
	v_addc_co_u32_e32 v31, vcc, 0, v29, vcc
	v_add_co_u32_e32 v32, vcc, s9, v28
	s_mov_b32 s9, 0x223000
	s_nop 0
	v_addc_co_u32_e32 v33, vcc, 0, v29, vcc
	global_load_dwordx4 v[44:47], v[30:31], off
	global_load_dwordx4 v[48:51], v[32:33], off
	v_add_co_u32_e32 v30, vcc, s9, v28
	s_mov_b32 s9, 0x2ab000
	s_nop 0
	v_addc_co_u32_e32 v31, vcc, 0, v29, vcc
	v_add_co_u32_e32 v32, vcc, s9, v28
	s_mov_b32 s9, 0x333000
	s_nop 0
	v_addc_co_u32_e32 v33, vcc, 0, v29, vcc
	global_load_dwordx4 v[52:55], v[30:31], off
	global_load_dwordx4 v[56:59], v[32:33], off
	v_add_co_u32_e32 v30, vcc, s9, v28
	s_mov_b32 s9, 0x3bb000
	s_nop 0
	v_addc_co_u32_e32 v31, vcc, 0, v29, vcc
	v_add_co_u32_e32 v28, vcc, s9, v28
	s_mov_b32 s9, 0
	s_nop 0
	v_addc_co_u32_e32 v29, vcc, 0, v29, vcc
	global_load_dwordx4 v[60:63], v[30:31], off
	global_load_dwordx4 v[64:67], v[28:29], off
	v_mov_b32_e32 v93, s45
	s_waitcnt lgkmcnt(0)
	s_barrier
	s_waitcnt vmcnt(16)
	v_mov_b32_e32 v30, v70
	s_waitcnt vmcnt(14)
	v_mov_b32_e32 v31, v10
	s_waitcnt vmcnt(12)
	v_mov_b32_e32 v28, v74
	v_mov_b32_e32 v10, v71
	v_mov_b32_e32 v32, v72
	v_mov_b32_e32 v34, v68
	v_mov_b32_e32 v35, v8
	v_mov_b32_e32 v8, v69
	v_mov_b32_e32 v68, v82
	v_mov_b32_e32 v70, v78
	v_mov_b32_e32 v71, v6
	v_mov_b32_e32 v6, v79
	v_mov_b32_e32 v72, v80
	v_mov_b32_e32 v74, v76
	v_mov_b32_e32 v76, v115
	s_waitcnt vmcnt(11)
	v_mov_b32_e32 v69, v14
	s_waitcnt vmcnt(10)
	v_mov_b32_e32 v29, v18
	v_mov_b32_e32 v18, v75
	v_mov_b32_e32 v33, v16
	v_mov_b32_e32 v16, v73
	v_mov_b32_e32 v14, v83
	v_mov_b32_e32 v73, v12
	v_mov_b32_e32 v12, v81
	v_mov_b32_e32 v75, v4
	v_mov_b32_e32 v4, v77
	v_mov_b32_e32 v77, v94
